# attention unit epilogue: the xor-1/2/4/8 hops of each row's 32-lane sum use DPP adds instead of serialized ds_bpermute+lgkmcnt(0) (same operands per add); plus P7 hoist and b64 accumulator clear
# speedup vs baseline: 1.0031x; 1.0031x over previous
.LBB0_1029:
	s_or_b64 exec, exec, s[0:1]
	s_waitcnt lgkmcnt(0)
	v_add_u32_e32 v64, s33, v188
	ds_read_b128 v[76:79], v64
	ds_read_b128 v[72:75], v64 offset:32
	ds_read_b128 v[68:71], v64 offset:64
	ds_read_b128 v[64:67], v64 offset:96
	s_waitcnt vmcnt(0) lgkmcnt(0)
	s_barrier
	flat_load_dword v84, v[150:151]
	flat_load_dword v85, v[150:151] offset:128
	flat_load_dword v86, v[150:151] offset:256
	flat_load_dword v87, v[150:151] offset:384
	ds_read_u16 v81, v222
	v_and_b32_e32 v80, 64, v209
	v_rcp_f32_e32 v76, v76
	v_add_u32_e32 v83, 64, v80
	ds_read_u16 v80, v221
	ds_read_u16 v82, v221 offset:128
	ds_read_u16 v88, v222 offset:128
	s_waitcnt lgkmcnt(0)
	v_lshlrev_b32_e32 v81, 16, v81
	v_mul_f32_e32 v48, v210, v48
	v_fma_f32 v89, -v48, v76, v81
	v_lshlrev_b32_e32 v48, 16, v80
	v_mul_f32_e32 v32, v210, v32
	v_fma_f32 v90, -v32, v76, v48
	v_lshlrev_b32_e32 v32, 16, v88
	v_mul_f32_e32 v16, v210, v16
	v_fma_f32 v88, -v16, v76, v32
	v_lshlrev_b32_e32 v16, 16, v82
	v_mul_f32_e32 v0, v210, v0
	v_mul_f32_e32 v48, v90, v90
	v_fma_f32 v91, -v0, v76, v16
	v_xor_b32_e32 v0, 1, v209
	v_fmac_f32_e32 v48, v89, v89
	v_cmp_lt_i32_e32 vcc, v0, v83
	v_fmac_f32_e32 v48, v88, v88
	v_fmac_f32_e32 v48, v91, v91
	v_cndmask_b32_e32 v0, v209, v0, vcc
	v_lshlrev_b32_e32 v32, 2, v0
	s_nop 1
	v_xor_b32_e32 v16, 2, v209
	v_cmp_lt_i32_e32 vcc, v16, v83
	v_rcp_f32_e32 v77, v77
	v_mul_f32_e32 v49, v210, v49
	v_cndmask_b32_e32 v16, v209, v16, vcc
	s_waitcnt lgkmcnt(0)
	v_add_f32_dpp v0, v48, v48 quad_perm:[1,0,3,2] row_mask:0xf bank_mask:0xf
	v_lshlrev_b32_e32 v80, 2, v16
	s_nop 1
	v_mul_f32_e32 v33, v210, v33
	v_mul_f32_e32 v17, v210, v17
	v_mul_f32_e32 v1, v210, v1
	v_mul_f32_e32 v34, v210, v34
	s_waitcnt lgkmcnt(0)
	v_add_f32_dpp v0, v0, v0 quad_perm:[2,3,0,1] row_mask:0xf bank_mask:0xf
	v_xor_b32_e32 v16, 4, v209
	v_cmp_lt_i32_e32 vcc, v16, v83
	v_mul_f32_e32 v50, v210, v50
	v_mul_f32_e32 v18, v210, v18
	v_cndmask_b32_e32 v16, v209, v16, vcc
	v_lshlrev_b32_e32 v81, 2, v16
	s_nop 1
	v_mul_f32_e32 v2, v210, v2
	v_mul_f32_e32 v35, v210, v35
	v_mul_f32_e32 v19, v210, v19
	v_mul_f32_e32 v3, v210, v3
	s_waitcnt lgkmcnt(0)
	v_add_f32_dpp v0, v0, v0 row_half_mirror row_mask:0xf bank_mask:0xf
	v_xor_b32_e32 v16, 8, v209
	v_cmp_lt_i32_e32 vcc, v16, v83
	v_mul_f32_e32 v20, v210, v20
	v_mul_f32_e32 v4, v210, v4
	v_cndmask_b32_e32 v16, v209, v16, vcc
	v_lshlrev_b32_e32 v82, 2, v16
	s_nop 1
	v_mul_f32_e32 v5, v210, v5
	v_mul_f32_e32 v6, v210, v6
	v_mul_f32_e32 v7, v210, v7
	v_mul_f32_e32 v8, v210, v8
	s_waitcnt lgkmcnt(0)
	v_add_f32_dpp v0, v0, v0 row_mirror row_mask:0xf bank_mask:0xf
	v_xor_b32_e32 v16, 16, v209
	v_cmp_lt_i32_e32 vcc, v16, v83
	s_lshl_b32 s2, s2, 1
	s_add_i32 s73, s73, s82
	v_cndmask_b32_e32 v16, v209, v16, vcc
	v_lshlrev_b32_e32 v83, 2, v16
	ds_bpermute_b32 v16, v83, v0
	s_add_i32 s68, s68, s69
	s_cmpk_gt_i32 s73, 0x7ff
	s_waitcnt lgkmcnt(0)
	v_add_f32_e32 v0, v0, v16
	v_fmamk_f32 v0, v0, 0x3c000000, v198
	v_mul_f32_e32 v16, 0x4f800000, v0
	v_cmp_gt_f32_e32 vcc, s72, v0
	s_nop 1
	v_cndmask_b32_e32 v0, v0, v16, vcc
	v_sqrt_f32_e32 v16, v0
	s_nop 0
	v_add_u32_e32 v48, -1, v16
	v_add_u32_e32 v76, 1, v16
	v_fma_f32 v92, -v48, v16, v0
	v_fma_f32 v93, -v76, v16, v0
	v_cmp_ge_f32_e64 s[0:1], 0, v92
	s_nop 1
	v_cndmask_b32_e64 v16, v16, v48, s[0:1]
	v_cmp_lt_f32_e64 s[0:1], 0, v93
	s_nop 1
	v_cndmask_b32_e64 v16, v16, v76, s[0:1]
	v_mul_f32_e32 v48, 0x37800000, v16
	v_cndmask_b32_e32 v16, v16, v48, vcc
	v_cmp_class_f32_e32 vcc, v0, v199
	s_waitcnt vmcnt(0)
	v_mul_f32_e32 v48, 0x3f4ccccd, v84
	v_mul_f32_e32 v76, 0x3f4ccccd, v85
	v_cndmask_b32_e32 v84, v16, v0, vcc
	v_div_scale_f32 v92, s[0:1], v84, v84, 1.0
	v_rcp_f32_e32 v93, v92
	v_mul_f32_e32 v16, 0x3f4ccccd, v86
	v_mul_f32_e32 v0, 0x3f4ccccd, v87
	v_fma_f32 v85, -v92, v93, 1.0
	v_fmac_f32_e32 v93, v85, v93
	v_div_scale_f32 v85, vcc, 1.0, v84, 1.0
	v_mul_f32_e32 v86, v85, v93
	v_fma_f32 v87, -v92, v86, v85
	v_fmac_f32_e32 v86, v87, v93
	v_fma_f32 v85, -v92, v86, v85
	v_div_fmas_f32 v85, v85, v93, v86
	v_div_fixup_f32 v84, v85, v84, 1.0
	v_mul_f32_e32 v85, v89, v84
	v_mul_f32_e32 v85, v48, v85
	v_cvt_pk_bf16_f32 v85, v85, v133
	ds_write_b16 v222, v85
	v_mul_f32_e32 v85, v90, v84
	v_mul_f32_e32 v85, v76, v85
	v_cvt_pk_bf16_f32 v85, v85, v133
	ds_write_b16 v221, v85
	v_mul_f32_e32 v85, v88, v84
	v_mul_f32_e32 v85, v16, v85
	v_mul_f32_e32 v84, v91, v84
	v_cvt_pk_bf16_f32 v85, v85, v133
	v_mul_f32_e32 v84, v0, v84
	ds_write_b16 v222, v85 offset:128
	v_cvt_pk_bf16_f32 v84, v84, v133
	ds_read_u16 v85, v220 offset:256
	ds_read_u16 v86, v219 offset:256
	ds_read_u16 v87, v219 offset:384
	ds_read_u16 v88, v220 offset:384
	ds_write_b16 v221, v84 offset:128
	s_waitcnt lgkmcnt(4)
	v_lshlrev_b32_e32 v85, 16, v85
	v_fma_f32 v49, -v49, v77, v85
	s_waitcnt lgkmcnt(3)
	v_lshlrev_b32_e32 v85, 16, v86
	v_fma_f32 v33, -v33, v77, v85
	v_mul_f32_e32 v85, v33, v33
	s_waitcnt lgkmcnt(1)
	v_lshlrev_b32_e32 v86, 16, v88
	v_fmac_f32_e32 v85, v49, v49
	v_fma_f32 v17, -v17, v77, v86
	v_lshlrev_b32_e32 v86, 16, v87
	v_fmac_f32_e32 v85, v17, v17
	v_fma_f32 v1, -v1, v77, v86
	v_fmac_f32_e32 v85, v1, v1
	s_nop 1
	s_waitcnt lgkmcnt(0)
	v_add_f32_dpp v77, v85, v85 quad_perm:[1,0,3,2] row_mask:0xf bank_mask:0xf
	s_nop 1
	s_waitcnt lgkmcnt(0)
	v_add_f32_dpp v77, v77, v77 quad_perm:[2,3,0,1] row_mask:0xf bank_mask:0xf
	s_nop 1
	s_waitcnt lgkmcnt(0)
	v_add_f32_dpp v77, v77, v77 row_half_mirror row_mask:0xf bank_mask:0xf
	s_nop 1
	s_waitcnt lgkmcnt(0)
	v_add_f32_dpp v77, v77, v77 row_mirror row_mask:0xf bank_mask:0xf
	ds_bpermute_b32 v85, v83, v77
	s_waitcnt lgkmcnt(0)
	v_add_f32_e32 v77, v77, v85
	v_fmamk_f32 v77, v77, 0x3c000000, v198
	v_mul_f32_e32 v85, 0x4f800000, v77
	v_cmp_gt_f32_e32 vcc, s72, v77
	s_nop 1
	v_cndmask_b32_e32 v77, v77, v85, vcc
	v_sqrt_f32_e32 v85, v77
	s_nop 0
	v_add_u32_e32 v86, -1, v85
	v_fma_f32 v87, -v86, v85, v77
	v_cmp_ge_f32_e64 s[0:1], 0, v87
	v_add_u32_e32 v87, 1, v85
	s_nop 0
	v_cndmask_b32_e64 v86, v85, v86, s[0:1]
	v_fma_f32 v85, -v87, v85, v77
	v_cmp_lt_f32_e64 s[0:1], 0, v85
	s_nop 1
	v_cndmask_b32_e64 v85, v86, v87, s[0:1]
	v_mul_f32_e32 v86, 0x37800000, v85
	v_cndmask_b32_e32 v85, v85, v86, vcc
	v_cmp_class_f32_e32 vcc, v77, v199
	s_nop 1
	v_cndmask_b32_e32 v77, v85, v77, vcc
	v_div_scale_f32 v85, s[0:1], v77, v77, 1.0
	v_rcp_f32_e32 v86, v85
	s_nop 0
	v_fma_f32 v84, -v85, v86, 1.0
	v_fmac_f32_e32 v86, v84, v86
	v_div_scale_f32 v84, vcc, 1.0, v77, 1.0
	v_mul_f32_e32 v87, v84, v86
	v_fma_f32 v88, -v85, v87, v84
	v_fmac_f32_e32 v87, v88, v86
	v_fma_f32 v84, -v85, v87, v84
	v_div_fmas_f32 v84, v84, v86, v87
	v_div_fixup_f32 v77, v84, v77, 1.0
	v_mul_f32_e32 v49, v49, v77
	v_mul_f32_e32 v33, v33, v77
	v_mul_f32_e32 v17, v17, v77
	v_mul_f32_e32 v49, v48, v49
	v_mul_f32_e32 v33, v76, v33
	v_mul_f32_e32 v17, v16, v17
	v_mul_f32_e32 v1, v1, v77
	v_cvt_pk_bf16_f32 v49, v49, v133
	ds_write_b16 v220, v49 offset:256
	v_cvt_pk_bf16_f32 v33, v33, v133
	ds_write_b16 v219, v33 offset:256
	v_cvt_pk_bf16_f32 v17, v17, v133
	v_mul_f32_e32 v1, v0, v1
	ds_write_b16 v220, v17 offset:384
	v_cvt_pk_bf16_f32 v1, v1, v133
	ds_read_u16 v17, v218 offset:512
	v_rcp_f32_e32 v33, v78
	ds_read_u16 v49, v217 offset:512
	ds_read_u16 v77, v217 offset:640
	ds_read_u16 v78, v218 offset:640
	ds_write_b16 v219, v1 offset:384
	s_waitcnt lgkmcnt(3)
	v_lshlrev_b32_e32 v49, 16, v49
	v_lshlrev_b32_e32 v17, 16, v17
	v_fma_f32 v34, -v34, v33, v49
	v_fma_f32 v17, -v50, v33, v17
	v_mul_f32_e32 v49, v34, v34
	s_waitcnt lgkmcnt(1)
	v_lshlrev_b32_e32 v50, 16, v78
	v_fmac_f32_e32 v49, v17, v17
	v_fma_f32 v18, -v18, v33, v50
	v_lshlrev_b32_e32 v50, 16, v77
	v_fmac_f32_e32 v49, v18, v18
	v_fma_f32 v2, -v2, v33, v50
	v_fmac_f32_e32 v49, v2, v2
	s_nop 1
	s_waitcnt lgkmcnt(0)
	v_add_f32_dpp v33, v49, v49 quad_perm:[1,0,3,2] row_mask:0xf bank_mask:0xf
	s_nop 1
	s_waitcnt lgkmcnt(0)
	v_add_f32_dpp v33, v33, v33 quad_perm:[2,3,0,1] row_mask:0xf bank_mask:0xf
	s_nop 1
	s_waitcnt lgkmcnt(0)
	v_add_f32_dpp v33, v33, v33 row_half_mirror row_mask:0xf bank_mask:0xf
	s_nop 1
	s_waitcnt lgkmcnt(0)
	v_add_f32_dpp v33, v33, v33 row_mirror row_mask:0xf bank_mask:0xf
	ds_bpermute_b32 v49, v83, v33
	s_waitcnt lgkmcnt(0)
	v_add_f32_e32 v33, v33, v49
	v_fmamk_f32 v33, v33, 0x3c000000, v198
	v_mul_f32_e32 v49, 0x4f800000, v33
	v_cmp_gt_f32_e32 vcc, s72, v33
	s_nop 1
	v_cndmask_b32_e32 v33, v33, v49, vcc
	v_sqrt_f32_e32 v49, v33
	s_nop 0
	v_add_u32_e32 v50, -1, v49
	v_fma_f32 v77, -v50, v49, v33
	v_cmp_ge_f32_e64 s[0:1], 0, v77
	v_add_u32_e32 v77, 1, v49
	s_nop 0
	v_cndmask_b32_e64 v50, v49, v50, s[0:1]
	v_fma_f32 v49, -v77, v49, v33
	v_cmp_lt_f32_e64 s[0:1], 0, v49
	s_nop 1
	v_cndmask_b32_e64 v49, v50, v77, s[0:1]
	v_mul_f32_e32 v50, 0x37800000, v49
	v_cndmask_b32_e32 v49, v49, v50, vcc
	v_cmp_class_f32_e32 vcc, v33, v199
	s_nop 1
	v_cndmask_b32_e32 v33, v49, v33, vcc
	v_div_scale_f32 v49, s[0:1], v33, v33, 1.0
	v_rcp_f32_e32 v50, v49
	s_nop 0
	v_fma_f32 v1, -v49, v50, 1.0
	v_fmac_f32_e32 v50, v1, v50
	v_div_scale_f32 v1, vcc, 1.0, v33, 1.0
	v_mul_f32_e32 v77, v1, v50
	v_fma_f32 v78, -v49, v77, v1
	v_fmac_f32_e32 v77, v78, v50
	v_fma_f32 v1, -v49, v77, v1
	v_div_fmas_f32 v1, v1, v50, v77
	v_div_fixup_f32 v1, v1, v33, 1.0
	v_mul_f32_e32 v17, v17, v1
	v_mul_f32_e32 v17, v48, v17
	v_cvt_pk_bf16_f32 v17, v17, v133
	ds_write_b16 v218, v17 offset:512
	v_mul_f32_e32 v17, v34, v1
	v_mul_f32_e32 v17, v76, v17
	v_cvt_pk_bf16_f32 v17, v17, v133
	ds_write_b16 v217, v17 offset:512
	v_mul_f32_e32 v17, v18, v1
	v_mul_f32_e32 v1, v2, v1
	v_mul_f32_e32 v17, v16, v17
	v_mul_f32_e32 v1, v0, v1
	v_cvt_pk_bf16_f32 v17, v17, v133
	ds_write_b16 v218, v17 offset:640
	v_cvt_pk_bf16_f32 v1, v1, v133
	ds_read_u16 v2, v215 offset:768
	v_rcp_f32_e32 v17, v79
	ds_read_u16 v18, v216 offset:768
	ds_read_u16 v33, v216 offset:896
	ds_read_u16 v34, v215 offset:896
	v_mul_f32_e32 v49, v210, v51
	ds_write_b16 v217, v1 offset:640
	s_waitcnt lgkmcnt(3)
	v_lshlrev_b32_e32 v18, 16, v18
	v_lshlrev_b32_e32 v2, 16, v2
	v_fma_f32 v18, -v35, v17, v18
	v_fma_f32 v2, -v49, v17, v2
	v_mul_f32_e32 v35, v18, v18
	s_waitcnt lgkmcnt(1)
	v_lshlrev_b32_e32 v34, 16, v34
	v_fmac_f32_e32 v35, v2, v2
	v_fma_f32 v19, -v19, v17, v34
	v_lshlrev_b32_e32 v33, 16, v33
	v_fmac_f32_e32 v35, v19, v19
	v_fma_f32 v3, -v3, v17, v33
	v_fmac_f32_e32 v35, v3, v3
	s_nop 1
	s_waitcnt lgkmcnt(0)
	v_add_f32_dpp v17, v35, v35 quad_perm:[1,0,3,2] row_mask:0xf bank_mask:0xf
	s_nop 1
	s_waitcnt lgkmcnt(0)
	v_add_f32_dpp v17, v17, v17 quad_perm:[2,3,0,1] row_mask:0xf bank_mask:0xf
	s_nop 1
	s_waitcnt lgkmcnt(0)
	v_add_f32_dpp v17, v17, v17 row_half_mirror row_mask:0xf bank_mask:0xf
	s_nop 1
	s_waitcnt lgkmcnt(0)
	v_add_f32_dpp v17, v17, v17 row_mirror row_mask:0xf bank_mask:0xf
	ds_bpermute_b32 v33, v83, v17
	s_waitcnt lgkmcnt(0)
	v_add_f32_e32 v17, v17, v33
	v_fmamk_f32 v17, v17, 0x3c000000, v198
	v_mul_f32_e32 v33, 0x4f800000, v17
	v_cmp_gt_f32_e32 vcc, s72, v17
	s_nop 1
	v_cndmask_b32_e32 v17, v17, v33, vcc
	v_sqrt_f32_e32 v33, v17
	s_nop 0
	v_add_u32_e32 v34, -1, v33
	v_fma_f32 v35, -v34, v33, v17
	v_cmp_ge_f32_e64 s[0:1], 0, v35
	v_add_u32_e32 v35, 1, v33
	s_nop 0
	v_cndmask_b32_e64 v34, v33, v34, s[0:1]
	v_fma_f32 v33, -v35, v33, v17
	v_cmp_lt_f32_e64 s[0:1], 0, v33
	s_nop 1
	v_cndmask_b32_e64 v33, v34, v35, s[0:1]
	v_mul_f32_e32 v34, 0x37800000, v33
	v_cndmask_b32_e32 v33, v33, v34, vcc
	v_cmp_class_f32_e32 vcc, v17, v199
	s_nop 1
	v_cndmask_b32_e32 v17, v33, v17, vcc
	v_div_scale_f32 v33, s[0:1], v17, v17, 1.0
	v_rcp_f32_e32 v34, v33
	s_nop 0
	v_fma_f32 v1, -v33, v34, 1.0
	v_fmac_f32_e32 v34, v1, v34
	v_div_scale_f32 v1, vcc, 1.0, v17, 1.0
	v_mul_f32_e32 v35, v1, v34
	v_fma_f32 v49, -v33, v35, v1
	v_fmac_f32_e32 v35, v49, v34
	v_fma_f32 v1, -v33, v35, v1
	v_div_fmas_f32 v1, v1, v34, v35
	v_div_fixup_f32 v1, v1, v17, 1.0
	v_mul_f32_e32 v2, v2, v1
	v_mul_f32_e32 v2, v48, v2
	v_cvt_pk_bf16_f32 v2, v2, v133
	ds_write_b16 v215, v2 offset:768
	v_mul_f32_e32 v2, v18, v1
	v_mul_f32_e32 v2, v76, v2
	v_cvt_pk_bf16_f32 v2, v2, v133
	ds_write_b16 v216, v2 offset:768
	v_mul_f32_e32 v2, v19, v1
	v_mul_f32_e32 v2, v16, v2
	v_mul_f32_e32 v1, v3, v1
	v_cvt_pk_bf16_f32 v2, v2, v133
	v_mul_f32_e32 v1, v0, v1
	ds_write_b16 v215, v2 offset:896
	v_cvt_pk_bf16_f32 v1, v1, v133
	ds_read_u16 v2, v222 offset:2176
	v_rcp_f32_e32 v3, v72
	ds_read_u16 v17, v221 offset:2176
	ds_read_u16 v18, v221 offset:2048
	ds_read_u16 v19, v222 offset:2048
	v_mul_f32_e32 v33, v210, v52
	ds_write_b16 v216, v1 offset:896
	s_waitcnt lgkmcnt(4)
	v_lshlrev_b32_e32 v2, 16, v2
	v_fma_f32 v2, -v33, v3, v2
	s_waitcnt lgkmcnt(3)
	v_lshlrev_b32_e32 v17, 16, v17
	v_mul_f32_e32 v33, v210, v36
	v_fma_f32 v17, -v33, v3, v17
	v_mul_f32_e32 v33, v17, v17
	s_waitcnt lgkmcnt(1)
	v_lshlrev_b32_e32 v19, 16, v19
	v_fmac_f32_e32 v33, v2, v2
	v_fma_f32 v19, -v20, v3, v19
	v_lshlrev_b32_e32 v18, 16, v18
	v_fmac_f32_e32 v33, v19, v19
	v_fma_f32 v3, -v4, v3, v18
	v_fmac_f32_e32 v33, v3, v3
	s_nop 1
	s_waitcnt lgkmcnt(0)
	v_add_f32_dpp v4, v33, v33 quad_perm:[1,0,3,2] row_mask:0xf bank_mask:0xf
	s_nop 1
	s_waitcnt lgkmcnt(0)
	v_add_f32_dpp v4, v4, v4 quad_perm:[2,3,0,1] row_mask:0xf bank_mask:0xf
	s_nop 1
	s_waitcnt lgkmcnt(0)
	v_add_f32_dpp v4, v4, v4 row_half_mirror row_mask:0xf bank_mask:0xf
	s_nop 1
	s_waitcnt lgkmcnt(0)
	v_add_f32_dpp v4, v4, v4 row_mirror row_mask:0xf bank_mask:0xf
	ds_bpermute_b32 v18, v83, v4
	s_waitcnt lgkmcnt(0)
	v_add_f32_e32 v4, v4, v18
	v_fmamk_f32 v4, v4, 0x3c000000, v198
	v_mul_f32_e32 v18, 0x4f800000, v4
	v_cmp_gt_f32_e32 vcc, s72, v4
	s_nop 1
	v_cndmask_b32_e32 v4, v4, v18, vcc
	v_sqrt_f32_e32 v18, v4
	s_nop 0
	v_add_u32_e32 v20, -1, v18
	v_fma_f32 v33, -v20, v18, v4
	v_cmp_ge_f32_e64 s[0:1], 0, v33
	v_add_u32_e32 v33, 1, v18
	s_nop 0
	v_cndmask_b32_e64 v20, v18, v20, s[0:1]
	v_fma_f32 v18, -v33, v18, v4
	v_cmp_lt_f32_e64 s[0:1], 0, v18
	s_nop 1
	v_cndmask_b32_e64 v18, v20, v33, s[0:1]
	v_mul_f32_e32 v20, 0x37800000, v18
	v_cndmask_b32_e32 v18, v18, v20, vcc
	v_cmp_class_f32_e32 vcc, v4, v199
	s_nop 1
	v_cndmask_b32_e32 v4, v18, v4, vcc
	v_div_scale_f32 v18, s[0:1], v4, v4, 1.0
	v_rcp_f32_e32 v20, v18
	s_nop 0
	v_fma_f32 v1, -v18, v20, 1.0
	v_fmac_f32_e32 v20, v1, v20
	v_div_scale_f32 v1, vcc, 1.0, v4, 1.0
	v_mul_f32_e32 v33, v1, v20
	v_fma_f32 v34, -v18, v33, v1
	v_fmac_f32_e32 v33, v34, v20
	v_fma_f32 v1, -v18, v33, v1
	v_div_fmas_f32 v1, v1, v20, v33
	v_div_fixup_f32 v1, v1, v4, 1.0
	v_mul_f32_e32 v2, v2, v1
	v_mul_f32_e32 v2, v48, v2
	v_cvt_pk_bf16_f32 v2, v2, v133
	ds_write_b16 v222, v2 offset:2176
	v_mul_f32_e32 v2, v17, v1
	v_mul_f32_e32 v2, v76, v2
	v_cvt_pk_bf16_f32 v2, v2, v133
	ds_write_b16 v221, v2 offset:2176
	v_mul_f32_e32 v2, v19, v1
	v_mul_f32_e32 v2, v16, v2
	v_mul_f32_e32 v1, v3, v1
	v_cvt_pk_bf16_f32 v2, v2, v133
	v_mul_f32_e32 v1, v0, v1
	ds_write_b16 v222, v2 offset:2048
	v_cvt_pk_bf16_f32 v1, v1, v133
	ds_read_u16 v2, v220 offset:2432
	v_rcp_f32_e32 v3, v73
	ds_read_u16 v4, v219 offset:2432
	ds_read_u16 v17, v219 offset:2304
	ds_read_u16 v18, v220 offset:2304
	v_mul_f32_e32 v19, v210, v53
	v_mul_f32_e32 v20, v210, v21
	s_waitcnt lgkmcnt(3)
	v_lshlrev_b32_e32 v2, 16, v2
	v_fma_f32 v2, -v19, v3, v2
	s_waitcnt lgkmcnt(2)
	v_lshlrev_b32_e32 v4, 16, v4
	v_mul_f32_e32 v19, v210, v37
	v_fma_f32 v4, -v19, v3, v4
	v_mul_f32_e32 v19, v4, v4
	s_waitcnt lgkmcnt(0)
	v_lshlrev_b32_e32 v18, 16, v18
	v_fmac_f32_e32 v19, v2, v2
	v_fma_f32 v18, -v20, v3, v18
	v_lshlrev_b32_e32 v17, 16, v17
	v_fmac_f32_e32 v19, v18, v18
	v_fma_f32 v3, -v5, v3, v17
	v_fmac_f32_e32 v19, v3, v3
	s_nop 1
	ds_write_b16 v221, v1 offset:2048
	s_waitcnt lgkmcnt(1)
	v_add_f32_dpp v5, v19, v19 quad_perm:[1,0,3,2] row_mask:0xf bank_mask:0xf
	s_nop 1
	s_waitcnt lgkmcnt(0)
	v_add_f32_dpp v5, v5, v5 quad_perm:[2,3,0,1] row_mask:0xf bank_mask:0xf
	s_nop 1
	s_waitcnt lgkmcnt(0)
	v_add_f32_dpp v5, v5, v5 row_half_mirror row_mask:0xf bank_mask:0xf
	s_nop 1
	s_waitcnt lgkmcnt(0)
	v_add_f32_dpp v5, v5, v5 row_mirror row_mask:0xf bank_mask:0xf
	ds_bpermute_b32 v17, v83, v5
	s_waitcnt lgkmcnt(0)
	v_add_f32_e32 v5, v5, v17
	v_fmamk_f32 v5, v5, 0x3c000000, v198
	v_mul_f32_e32 v17, 0x4f800000, v5
	v_cmp_gt_f32_e32 vcc, s72, v5
	s_nop 1
	v_cndmask_b32_e32 v5, v5, v17, vcc
	v_sqrt_f32_e32 v17, v5
	s_nop 0
	v_add_u32_e32 v19, -1, v17
	v_fma_f32 v20, -v19, v17, v5
	v_cmp_ge_f32_e64 s[0:1], 0, v20
	v_add_u32_e32 v20, 1, v17
	s_nop 0
	v_cndmask_b32_e64 v19, v17, v19, s[0:1]
	v_fma_f32 v17, -v20, v17, v5
	v_cmp_lt_f32_e64 s[0:1], 0, v17
	s_nop 1
	v_cndmask_b32_e64 v17, v19, v20, s[0:1]
	v_mul_f32_e32 v19, 0x37800000, v17
	v_cndmask_b32_e32 v17, v17, v19, vcc
	v_cmp_class_f32_e32 vcc, v5, v199
	s_nop 1
	v_cndmask_b32_e32 v5, v17, v5, vcc
	v_div_scale_f32 v17, s[0:1], v5, v5, 1.0
	v_rcp_f32_e32 v19, v17
	s_nop 0
	v_fma_f32 v1, -v17, v19, 1.0
	v_fmac_f32_e32 v19, v1, v19
	v_div_scale_f32 v1, vcc, 1.0, v5, 1.0
	v_mul_f32_e32 v20, v1, v19
	v_fma_f32 v21, -v17, v20, v1
	v_fmac_f32_e32 v20, v21, v19
	v_fma_f32 v1, -v17, v20, v1
	v_div_fmas_f32 v1, v1, v19, v20
	v_div_fixup_f32 v1, v1, v5, 1.0
	v_mul_f32_e32 v2, v2, v1
	v_mul_f32_e32 v2, v48, v2
	v_cvt_pk_bf16_f32 v2, v2, v133
	ds_write_b16 v220, v2 offset:2432
	v_mul_f32_e32 v2, v4, v1
	v_mul_f32_e32 v2, v76, v2
	v_cvt_pk_bf16_f32 v2, v2, v133
	ds_write_b16 v219, v2 offset:2432
	v_mul_f32_e32 v2, v18, v1
	v_mul_f32_e32 v2, v16, v2
	v_mul_f32_e32 v1, v3, v1
	v_cvt_pk_bf16_f32 v2, v2, v133
	v_mul_f32_e32 v1, v0, v1
	ds_write_b16 v220, v2 offset:2304
	v_cvt_pk_bf16_f32 v1, v1, v133
	ds_read_u16 v2, v218 offset:2688
	v_rcp_f32_e32 v3, v74
	ds_read_u16 v4, v217 offset:2688
	ds_read_u16 v5, v217 offset:2560
	ds_read_u16 v17, v218 offset:2560
	v_mul_f32_e32 v18, v210, v54
	v_mul_f32_e32 v19, v210, v22
	s_waitcnt lgkmcnt(3)
	v_lshlrev_b32_e32 v2, 16, v2
	v_fma_f32 v2, -v18, v3, v2
	s_waitcnt lgkmcnt(2)
	v_lshlrev_b32_e32 v4, 16, v4
	v_mul_f32_e32 v18, v210, v38
	v_fma_f32 v4, -v18, v3, v4
	v_mul_f32_e32 v18, v4, v4
	s_waitcnt lgkmcnt(0)
	v_lshlrev_b32_e32 v17, 16, v17
	v_fmac_f32_e32 v18, v2, v2
	v_fma_f32 v17, -v19, v3, v17
	v_lshlrev_b32_e32 v5, 16, v5
	v_fmac_f32_e32 v18, v17, v17
	v_fma_f32 v3, -v6, v3, v5
	v_fmac_f32_e32 v18, v3, v3
	s_nop 1
	ds_write_b16 v219, v1 offset:2304
	s_waitcnt lgkmcnt(1)
	v_add_f32_dpp v5, v18, v18 quad_perm:[1,0,3,2] row_mask:0xf bank_mask:0xf
	s_nop 1
	s_waitcnt lgkmcnt(0)
	v_add_f32_dpp v5, v5, v5 quad_perm:[2,3,0,1] row_mask:0xf bank_mask:0xf
	s_nop 1
	s_waitcnt lgkmcnt(0)
	v_add_f32_dpp v5, v5, v5 row_half_mirror row_mask:0xf bank_mask:0xf
	s_nop 1
	s_waitcnt lgkmcnt(0)
	v_add_f32_dpp v5, v5, v5 row_mirror row_mask:0xf bank_mask:0xf
	ds_bpermute_b32 v6, v83, v5
	s_waitcnt lgkmcnt(0)
	v_add_f32_e32 v5, v5, v6
	v_fmamk_f32 v5, v5, 0x3c000000, v198
	v_mul_f32_e32 v6, 0x4f800000, v5
	v_cmp_gt_f32_e32 vcc, s72, v5
	s_nop 1
	v_cndmask_b32_e32 v5, v5, v6, vcc
	v_sqrt_f32_e32 v6, v5
	s_nop 0
	v_add_u32_e32 v18, -1, v6
	v_fma_f32 v19, -v18, v6, v5
	v_cmp_ge_f32_e64 s[0:1], 0, v19
	v_add_u32_e32 v19, 1, v6
	s_nop 0
	v_cndmask_b32_e64 v18, v6, v18, s[0:1]
	v_fma_f32 v6, -v19, v6, v5
	v_cmp_lt_f32_e64 s[0:1], 0, v6
	s_nop 1
	v_cndmask_b32_e64 v6, v18, v19, s[0:1]
	v_mul_f32_e32 v18, 0x37800000, v6
	v_cndmask_b32_e32 v6, v6, v18, vcc
	v_cmp_class_f32_e32 vcc, v5, v199
	s_nop 1
	v_cndmask_b32_e32 v5, v6, v5, vcc
	v_div_scale_f32 v6, s[0:1], v5, v5, 1.0
	v_rcp_f32_e32 v18, v6
	s_nop 0
	v_fma_f32 v1, -v6, v18, 1.0
	v_fmac_f32_e32 v18, v1, v18
	v_div_scale_f32 v1, vcc, 1.0, v5, 1.0
	v_mul_f32_e32 v19, v1, v18
	v_fma_f32 v20, -v6, v19, v1
	v_fmac_f32_e32 v19, v20, v18
	v_fma_f32 v1, -v6, v19, v1
	v_div_fmas_f32 v1, v1, v18, v19
	v_div_fixup_f32 v1, v1, v5, 1.0
	v_mul_f32_e32 v2, v2, v1
	v_mul_f32_e32 v2, v48, v2
	v_cvt_pk_bf16_f32 v2, v2, v133
	ds_write_b16 v218, v2 offset:2688
	v_mul_f32_e32 v2, v4, v1
	v_mul_f32_e32 v2, v76, v2
	v_cvt_pk_bf16_f32 v2, v2, v133
	ds_write_b16 v217, v2 offset:2688
	v_mul_f32_e32 v2, v17, v1
	v_mul_f32_e32 v2, v16, v2
	v_mul_f32_e32 v1, v3, v1
	v_cvt_pk_bf16_f32 v2, v2, v133
	v_mul_f32_e32 v1, v0, v1
	ds_write_b16 v218, v2 offset:2560
	v_cvt_pk_bf16_f32 v1, v1, v133
	ds_read_u16 v2, v215 offset:2944
	v_rcp_f32_e32 v3, v75
	ds_read_u16 v4, v216 offset:2944
	ds_read_u16 v5, v216 offset:2816
	ds_read_u16 v6, v215 offset:2816
	v_mul_f32_e32 v17, v210, v55
	v_mul_f32_e32 v18, v210, v23
	s_waitcnt lgkmcnt(3)
	v_lshlrev_b32_e32 v2, 16, v2
	v_fma_f32 v2, -v17, v3, v2
	s_waitcnt lgkmcnt(2)
	v_lshlrev_b32_e32 v4, 16, v4
	v_mul_f32_e32 v17, v210, v39
	v_fma_f32 v4, -v17, v3, v4
	v_mul_f32_e32 v17, v4, v4
	s_waitcnt lgkmcnt(0)
	v_lshlrev_b32_e32 v6, 16, v6
	v_fmac_f32_e32 v17, v2, v2
	v_fma_f32 v6, -v18, v3, v6
	v_lshlrev_b32_e32 v5, 16, v5
	v_fmac_f32_e32 v17, v6, v6
	v_fma_f32 v3, -v7, v3, v5
	v_fmac_f32_e32 v17, v3, v3
	s_nop 1
	ds_write_b16 v217, v1 offset:2560
	s_waitcnt lgkmcnt(1)
	v_add_f32_dpp v5, v17, v17 quad_perm:[1,0,3,2] row_mask:0xf bank_mask:0xf
	s_nop 1
	s_waitcnt lgkmcnt(0)
	v_add_f32_dpp v5, v5, v5 quad_perm:[2,3,0,1] row_mask:0xf bank_mask:0xf
	s_nop 1
	s_waitcnt lgkmcnt(0)
	v_add_f32_dpp v5, v5, v5 row_half_mirror row_mask:0xf bank_mask:0xf
	s_nop 1
	s_waitcnt lgkmcnt(0)
	v_add_f32_dpp v5, v5, v5 row_mirror row_mask:0xf bank_mask:0xf
	ds_bpermute_b32 v7, v83, v5
	s_waitcnt lgkmcnt(0)
	v_add_f32_e32 v5, v5, v7
	v_fmamk_f32 v5, v5, 0x3c000000, v198
	v_mul_f32_e32 v7, 0x4f800000, v5
	v_cmp_gt_f32_e32 vcc, s72, v5
	s_nop 1
	v_cndmask_b32_e32 v5, v5, v7, vcc
	v_sqrt_f32_e32 v7, v5
	s_nop 0
	v_add_u32_e32 v17, -1, v7
	v_fma_f32 v18, -v17, v7, v5
	v_cmp_ge_f32_e64 s[0:1], 0, v18
	v_add_u32_e32 v18, 1, v7
	s_nop 0
	v_cndmask_b32_e64 v17, v7, v17, s[0:1]
	v_fma_f32 v7, -v18, v7, v5
	v_cmp_lt_f32_e64 s[0:1], 0, v7
	s_nop 1
	v_cndmask_b32_e64 v7, v17, v18, s[0:1]
	v_mul_f32_e32 v17, 0x37800000, v7
	v_cndmask_b32_e32 v7, v7, v17, vcc
	v_cmp_class_f32_e32 vcc, v5, v199
	s_nop 1
	v_cndmask_b32_e32 v5, v7, v5, vcc
	v_div_scale_f32 v7, s[0:1], v5, v5, 1.0
	v_rcp_f32_e32 v17, v7
	s_nop 0
	v_fma_f32 v1, -v7, v17, 1.0
	v_fmac_f32_e32 v17, v1, v17
	v_div_scale_f32 v1, vcc, 1.0, v5, 1.0
	v_mul_f32_e32 v18, v1, v17
	v_fma_f32 v19, -v7, v18, v1
	v_fmac_f32_e32 v18, v19, v17
	v_fma_f32 v1, -v7, v18, v1
	v_div_fmas_f32 v1, v1, v17, v18
	v_div_fixup_f32 v1, v1, v5, 1.0
	v_mul_f32_e32 v2, v2, v1
	v_mul_f32_e32 v2, v48, v2
	v_cvt_pk_bf16_f32 v2, v2, v133
	ds_write_b16 v215, v2 offset:2944
	v_mul_f32_e32 v2, v4, v1
	v_mul_f32_e32 v2, v76, v2
	v_cvt_pk_bf16_f32 v2, v2, v133
	ds_write_b16 v216, v2 offset:2944
	v_mul_f32_e32 v2, v6, v1
	v_mul_f32_e32 v2, v16, v2
	v_mul_f32_e32 v1, v3, v1
	v_cvt_pk_bf16_f32 v2, v2, v133
	v_mul_f32_e32 v1, v0, v1
	ds_write_b16 v215, v2 offset:2816
	v_cvt_pk_bf16_f32 v1, v1, v133
	ds_read_u16 v2, v222 offset:4096
	v_rcp_f32_e32 v3, v68
	ds_read_u16 v4, v221 offset:4096
	ds_read_u16 v5, v221 offset:4224
	ds_read_u16 v6, v222 offset:4224
	v_mul_f32_e32 v7, v210, v56
	v_mul_f32_e32 v17, v210, v24
	s_waitcnt lgkmcnt(3)
	v_lshlrev_b32_e32 v2, 16, v2
	v_fma_f32 v2, -v7, v3, v2
	s_waitcnt lgkmcnt(2)
	v_lshlrev_b32_e32 v4, 16, v4
	v_mul_f32_e32 v7, v210, v40
	v_fma_f32 v4, -v7, v3, v4
	v_mul_f32_e32 v7, v4, v4
	s_waitcnt lgkmcnt(0)
	v_lshlrev_b32_e32 v6, 16, v6
	v_fmac_f32_e32 v7, v2, v2
	v_fma_f32 v6, -v17, v3, v6
	v_lshlrev_b32_e32 v5, 16, v5
	v_fmac_f32_e32 v7, v6, v6
	v_fma_f32 v3, -v8, v3, v5
	v_fmac_f32_e32 v7, v3, v3
	s_nop 1
	ds_write_b16 v216, v1 offset:2816
	s_waitcnt lgkmcnt(1)
	v_add_f32_dpp v5, v7, v7 quad_perm:[1,0,3,2] row_mask:0xf bank_mask:0xf
	s_nop 1
	s_waitcnt lgkmcnt(0)
	v_add_f32_dpp v5, v5, v5 quad_perm:[2,3,0,1] row_mask:0xf bank_mask:0xf
	s_nop 1
	s_waitcnt lgkmcnt(0)
	v_add_f32_dpp v5, v5, v5 row_half_mirror row_mask:0xf bank_mask:0xf
	s_nop 1
	s_waitcnt lgkmcnt(0)
	v_add_f32_dpp v5, v5, v5 row_mirror row_mask:0xf bank_mask:0xf
	ds_bpermute_b32 v7, v83, v5
	s_waitcnt lgkmcnt(0)
	v_add_f32_e32 v5, v5, v7
	v_fmamk_f32 v5, v5, 0x3c000000, v198
	v_mul_f32_e32 v7, 0x4f800000, v5
	v_cmp_gt_f32_e32 vcc, s72, v5
	s_nop 1
	v_cndmask_b32_e32 v5, v5, v7, vcc
	v_sqrt_f32_e32 v7, v5
	s_nop 0
	v_add_u32_e32 v8, -1, v7
	v_fma_f32 v17, -v8, v7, v5
	v_cmp_ge_f32_e64 s[0:1], 0, v17
	v_add_u32_e32 v17, 1, v7
	s_nop 0
	v_cndmask_b32_e64 v8, v7, v8, s[0:1]
	v_fma_f32 v7, -v17, v7, v5
	v_cmp_lt_f32_e64 s[0:1], 0, v7
	s_nop 1
	v_cndmask_b32_e64 v7, v8, v17, s[0:1]
	v_mul_f32_e32 v8, 0x37800000, v7
	v_cndmask_b32_e32 v7, v7, v8, vcc
	v_cmp_class_f32_e32 vcc, v5, v199
	s_nop 1
	v_cndmask_b32_e32 v5, v7, v5, vcc
	v_div_scale_f32 v7, s[0:1], v5, v5, 1.0
	v_rcp_f32_e32 v8, v7
	s_nop 0
	v_fma_f32 v1, -v7, v8, 1.0
	v_fmac_f32_e32 v8, v1, v8
	v_div_scale_f32 v1, vcc, 1.0, v5, 1.0
	v_mul_f32_e32 v17, v1, v8
	v_fma_f32 v18, -v7, v17, v1
	v_fmac_f32_e32 v17, v18, v8
	v_fma_f32 v1, -v7, v17, v1
	v_div_fmas_f32 v1, v1, v8, v17
	v_div_fixup_f32 v1, v1, v5, 1.0
	v_mul_f32_e32 v2, v2, v1
	v_mul_f32_e32 v2, v48, v2
	v_cvt_pk_bf16_f32 v2, v2, v133
	ds_write_b16 v222, v2 offset:4096
	v_mul_f32_e32 v2, v4, v1
	v_mul_f32_e32 v2, v76, v2
	v_cvt_pk_bf16_f32 v2, v2, v133
	ds_write_b16 v221, v2 offset:4096
	v_mul_f32_e32 v2, v6, v1
	v_mul_f32_e32 v2, v16, v2
	v_mul_f32_e32 v1, v3, v1
	v_cvt_pk_bf16_f32 v2, v2, v133
	v_mul_f32_e32 v1, v0, v1
	ds_write_b16 v222, v2 offset:4224
	v_cvt_pk_bf16_f32 v1, v1, v133
	ds_read_u16 v2, v220 offset:4352
	v_rcp_f32_e32 v3, v69
	ds_read_u16 v4, v219 offset:4352
	ds_read_u16 v5, v219 offset:4480
	ds_read_u16 v6, v220 offset:4480
	v_mul_f32_e32 v7, v210, v57
	v_mul_f32_e32 v8, v210, v25
	s_waitcnt lgkmcnt(3)
	v_lshlrev_b32_e32 v2, 16, v2
	v_fma_f32 v2, -v7, v3, v2
	s_waitcnt lgkmcnt(2)
	v_lshlrev_b32_e32 v4, 16, v4
	v_mul_f32_e32 v7, v210, v41
	v_fma_f32 v4, -v7, v3, v4
	v_mul_f32_e32 v7, v4, v4
	s_waitcnt lgkmcnt(0)
	v_lshlrev_b32_e32 v6, 16, v6
	v_fmac_f32_e32 v7, v2, v2
	v_fma_f32 v6, -v8, v3, v6
	v_lshlrev_b32_e32 v5, 16, v5
	v_mul_f32_e32 v8, v210, v9
	v_fmac_f32_e32 v7, v6, v6
	v_fma_f32 v3, -v8, v3, v5
	v_fmac_f32_e32 v7, v3, v3
	s_nop 1
	ds_write_b16 v221, v1 offset:4224
	s_waitcnt lgkmcnt(1)
	v_add_f32_dpp v5, v7, v7 quad_perm:[1,0,3,2] row_mask:0xf bank_mask:0xf
	s_nop 1
	s_waitcnt lgkmcnt(0)
	v_add_f32_dpp v5, v5, v5 quad_perm:[2,3,0,1] row_mask:0xf bank_mask:0xf
	s_nop 1
	s_waitcnt lgkmcnt(0)
	v_add_f32_dpp v5, v5, v5 row_half_mirror row_mask:0xf bank_mask:0xf
	s_nop 1
	s_waitcnt lgkmcnt(0)
	v_add_f32_dpp v5, v5, v5 row_mirror row_mask:0xf bank_mask:0xf
	ds_bpermute_b32 v7, v83, v5
	s_waitcnt lgkmcnt(0)
	v_add_f32_e32 v5, v5, v7
	v_fmamk_f32 v5, v5, 0x3c000000, v198
	v_mul_f32_e32 v7, 0x4f800000, v5
	v_cmp_gt_f32_e32 vcc, s72, v5
	s_nop 1
	v_cndmask_b32_e32 v5, v5, v7, vcc
	v_sqrt_f32_e32 v7, v5
	s_nop 0
	v_add_u32_e32 v8, -1, v7
	v_fma_f32 v9, -v8, v7, v5
	v_cmp_ge_f32_e64 s[0:1], 0, v9
	v_add_u32_e32 v9, 1, v7
	s_nop 0
	v_cndmask_b32_e64 v8, v7, v8, s[0:1]
	v_fma_f32 v7, -v9, v7, v5
	v_cmp_lt_f32_e64 s[0:1], 0, v7
	s_nop 1
	v_cndmask_b32_e64 v7, v8, v9, s[0:1]
	v_mul_f32_e32 v8, 0x37800000, v7
	v_cndmask_b32_e32 v7, v7, v8, vcc
	v_cmp_class_f32_e32 vcc, v5, v199
	s_nop 1
	v_cndmask_b32_e32 v5, v7, v5, vcc
	v_div_scale_f32 v7, s[0:1], v5, v5, 1.0
	v_rcp_f32_e32 v8, v7
	s_nop 0
	v_fma_f32 v1, -v7, v8, 1.0
	v_fmac_f32_e32 v8, v1, v8
	v_div_scale_f32 v1, vcc, 1.0, v5, 1.0
	v_mul_f32_e32 v9, v1, v8
	v_fma_f32 v17, -v7, v9, v1
	v_fmac_f32_e32 v9, v17, v8
	v_fma_f32 v1, -v7, v9, v1
	v_div_fmas_f32 v1, v1, v8, v9
	v_div_fixup_f32 v1, v1, v5, 1.0
	v_mul_f32_e32 v2, v2, v1
	v_mul_f32_e32 v2, v48, v2
	v_cvt_pk_bf16_f32 v2, v2, v133
	ds_write_b16 v220, v2 offset:4352
	v_mul_f32_e32 v2, v4, v1
	v_mul_f32_e32 v2, v76, v2
	v_cvt_pk_bf16_f32 v2, v2, v133
	ds_write_b16 v219, v2 offset:4352
	v_mul_f32_e32 v2, v6, v1
	v_mul_f32_e32 v2, v16, v2
	v_mul_f32_e32 v1, v3, v1
	v_cvt_pk_bf16_f32 v2, v2, v133
	v_mul_f32_e32 v1, v0, v1
	ds_write_b16 v220, v2 offset:4480
	v_cvt_pk_bf16_f32 v1, v1, v133
	ds_read_u16 v2, v218 offset:4608
	v_rcp_f32_e32 v3, v70
	ds_read_u16 v4, v217 offset:4608
	ds_read_u16 v5, v217 offset:4736
	ds_read_u16 v6, v218 offset:4736
	v_mul_f32_e32 v7, v210, v58
	v_mul_f32_e32 v8, v210, v26
	s_waitcnt lgkmcnt(3)
	v_lshlrev_b32_e32 v2, 16, v2
	v_fma_f32 v2, -v7, v3, v2
	s_waitcnt lgkmcnt(2)
	v_lshlrev_b32_e32 v4, 16, v4
	v_mul_f32_e32 v7, v210, v42
	v_fma_f32 v4, -v7, v3, v4
	v_mul_f32_e32 v7, v4, v4
	s_waitcnt lgkmcnt(0)
	v_lshlrev_b32_e32 v6, 16, v6
	v_fmac_f32_e32 v7, v2, v2
	v_fma_f32 v6, -v8, v3, v6
	v_lshlrev_b32_e32 v5, 16, v5
	v_mul_f32_e32 v8, v210, v10
	v_fmac_f32_e32 v7, v6, v6
	v_fma_f32 v3, -v8, v3, v5
	v_fmac_f32_e32 v7, v3, v3
	s_nop 1
	ds_write_b16 v219, v1 offset:4480
	s_waitcnt lgkmcnt(1)
	v_add_f32_dpp v5, v7, v7 quad_perm:[1,0,3,2] row_mask:0xf bank_mask:0xf
	s_nop 1
	s_waitcnt lgkmcnt(0)
	v_add_f32_dpp v5, v5, v5 quad_perm:[2,3,0,1] row_mask:0xf bank_mask:0xf
	s_nop 1
	s_waitcnt lgkmcnt(0)
	v_add_f32_dpp v5, v5, v5 row_half_mirror row_mask:0xf bank_mask:0xf
	s_nop 1
	s_waitcnt lgkmcnt(0)
	v_add_f32_dpp v5, v5, v5 row_mirror row_mask:0xf bank_mask:0xf
	ds_bpermute_b32 v7, v83, v5
	s_waitcnt lgkmcnt(0)
	v_add_f32_e32 v5, v5, v7
	v_fmamk_f32 v5, v5, 0x3c000000, v198
	v_mul_f32_e32 v7, 0x4f800000, v5
	v_cmp_gt_f32_e32 vcc, s72, v5
	s_nop 1
	v_cndmask_b32_e32 v5, v5, v7, vcc
	v_sqrt_f32_e32 v7, v5
	s_nop 0
	v_add_u32_e32 v8, -1, v7
	v_fma_f32 v9, -v8, v7, v5
	v_cmp_ge_f32_e64 s[0:1], 0, v9
	v_add_u32_e32 v9, 1, v7
	s_nop 0
	v_cndmask_b32_e64 v8, v7, v8, s[0:1]
	v_fma_f32 v7, -v9, v7, v5
	v_cmp_lt_f32_e64 s[0:1], 0, v7
	s_nop 1
	v_cndmask_b32_e64 v7, v8, v9, s[0:1]
	v_mul_f32_e32 v8, 0x37800000, v7
	v_cndmask_b32_e32 v7, v7, v8, vcc
	v_cmp_class_f32_e32 vcc, v5, v199
	s_nop 1
	v_cndmask_b32_e32 v5, v7, v5, vcc
	v_div_scale_f32 v7, s[0:1], v5, v5, 1.0
	v_rcp_f32_e32 v8, v7
	s_nop 0
	v_fma_f32 v1, -v7, v8, 1.0
	v_fmac_f32_e32 v8, v1, v8
	v_div_scale_f32 v1, vcc, 1.0, v5, 1.0
	v_mul_f32_e32 v9, v1, v8
	v_fma_f32 v10, -v7, v9, v1
	v_fmac_f32_e32 v9, v10, v8
	v_fma_f32 v1, -v7, v9, v1
	v_div_fmas_f32 v1, v1, v8, v9
	v_div_fixup_f32 v1, v1, v5, 1.0
	v_mul_f32_e32 v2, v2, v1
	v_mul_f32_e32 v2, v48, v2
	v_cvt_pk_bf16_f32 v2, v2, v133
	ds_write_b16 v218, v2 offset:4608
	v_mul_f32_e32 v2, v4, v1
	v_mul_f32_e32 v2, v76, v2
	v_cvt_pk_bf16_f32 v2, v2, v133
	ds_write_b16 v217, v2 offset:4608
	v_mul_f32_e32 v2, v6, v1
	v_mul_f32_e32 v2, v16, v2
	v_mul_f32_e32 v1, v3, v1
	v_cvt_pk_bf16_f32 v2, v2, v133
	v_mul_f32_e32 v1, v0, v1
	ds_write_b16 v218, v2 offset:4736
	v_cvt_pk_bf16_f32 v1, v1, v133
	ds_read_u16 v2, v215 offset:4864
	v_rcp_f32_e32 v3, v71
	ds_read_u16 v4, v216 offset:4864
	ds_read_u16 v5, v216 offset:4992
	ds_read_u16 v6, v215 offset:4992
	v_mul_f32_e32 v7, v210, v59
	v_mul_f32_e32 v8, v210, v27
	s_waitcnt lgkmcnt(3)
	v_lshlrev_b32_e32 v2, 16, v2
	v_fma_f32 v2, -v7, v3, v2
	s_waitcnt lgkmcnt(2)
	v_lshlrev_b32_e32 v4, 16, v4
	v_mul_f32_e32 v7, v210, v43
	v_fma_f32 v4, -v7, v3, v4
	v_mul_f32_e32 v7, v4, v4
	s_waitcnt lgkmcnt(0)
	v_lshlrev_b32_e32 v6, 16, v6
	v_fmac_f32_e32 v7, v2, v2
	v_fma_f32 v6, -v8, v3, v6
	v_lshlrev_b32_e32 v5, 16, v5
	v_mul_f32_e32 v8, v210, v11
	v_fmac_f32_e32 v7, v6, v6
	v_fma_f32 v3, -v8, v3, v5
	v_fmac_f32_e32 v7, v3, v3
	s_nop 1
	ds_write_b16 v217, v1 offset:4736
	s_waitcnt lgkmcnt(1)
	v_add_f32_dpp v5, v7, v7 quad_perm:[1,0,3,2] row_mask:0xf bank_mask:0xf
	s_nop 1
	s_waitcnt lgkmcnt(0)
	v_add_f32_dpp v5, v5, v5 quad_perm:[2,3,0,1] row_mask:0xf bank_mask:0xf
	s_nop 1
	s_waitcnt lgkmcnt(0)
	v_add_f32_dpp v5, v5, v5 row_half_mirror row_mask:0xf bank_mask:0xf
	s_nop 1
	s_waitcnt lgkmcnt(0)
	v_add_f32_dpp v5, v5, v5 row_mirror row_mask:0xf bank_mask:0xf
	ds_bpermute_b32 v7, v83, v5
	s_waitcnt lgkmcnt(0)
	v_add_f32_e32 v5, v5, v7
	v_fmamk_f32 v5, v5, 0x3c000000, v198
	v_mul_f32_e32 v7, 0x4f800000, v5
	v_cmp_gt_f32_e32 vcc, s72, v5
	s_nop 1
	v_cndmask_b32_e32 v5, v5, v7, vcc
	v_sqrt_f32_e32 v7, v5
	s_nop 0
	v_add_u32_e32 v8, -1, v7
	v_fma_f32 v9, -v8, v7, v5
	v_cmp_ge_f32_e64 s[0:1], 0, v9
	v_add_u32_e32 v9, 1, v7
	s_nop 0
	v_cndmask_b32_e64 v8, v7, v8, s[0:1]
	v_fma_f32 v7, -v9, v7, v5
	v_cmp_lt_f32_e64 s[0:1], 0, v7
	s_nop 1
	v_cndmask_b32_e64 v7, v8, v9, s[0:1]
	v_mul_f32_e32 v8, 0x37800000, v7
	v_cndmask_b32_e32 v7, v7, v8, vcc
	v_cmp_class_f32_e32 vcc, v5, v199
	s_nop 1
	v_cndmask_b32_e32 v5, v7, v5, vcc
	v_div_scale_f32 v7, s[0:1], v5, v5, 1.0
	v_rcp_f32_e32 v8, v7
	s_nop 0
	v_fma_f32 v1, -v7, v8, 1.0
	v_fmac_f32_e32 v8, v1, v8
	v_div_scale_f32 v1, vcc, 1.0, v5, 1.0
	v_mul_f32_e32 v9, v1, v8
	v_fma_f32 v10, -v7, v9, v1
	v_fmac_f32_e32 v9, v10, v8
	v_fma_f32 v1, -v7, v9, v1
	v_div_fmas_f32 v1, v1, v8, v9
	v_div_fixup_f32 v1, v1, v5, 1.0
	v_mul_f32_e32 v2, v2, v1
	v_mul_f32_e32 v2, v48, v2
	v_cvt_pk_bf16_f32 v2, v2, v133
	ds_write_b16 v215, v2 offset:4864
	v_mul_f32_e32 v2, v4, v1
	v_mul_f32_e32 v2, v76, v2
	v_cvt_pk_bf16_f32 v2, v2, v133
	ds_write_b16 v216, v2 offset:4864
	v_mul_f32_e32 v2, v6, v1
	v_mul_f32_e32 v2, v16, v2
	v_mul_f32_e32 v1, v3, v1
	v_cvt_pk_bf16_f32 v2, v2, v133
	v_mul_f32_e32 v1, v0, v1
	ds_write_b16 v215, v2 offset:4992
	v_cvt_pk_bf16_f32 v1, v1, v133
	ds_read_u16 v2, v222 offset:6272
	v_rcp_f32_e32 v3, v64
	ds_read_u16 v4, v221 offset:6272
	ds_read_u16 v5, v221 offset:6144
	ds_read_u16 v6, v222 offset:6144
	v_mul_f32_e32 v7, v210, v60
	v_mul_f32_e32 v8, v210, v28
	s_waitcnt lgkmcnt(3)
	v_lshlrev_b32_e32 v2, 16, v2
	v_fma_f32 v2, -v7, v3, v2
	s_waitcnt lgkmcnt(2)
	v_lshlrev_b32_e32 v4, 16, v4
	v_mul_f32_e32 v7, v210, v44
	v_fma_f32 v4, -v7, v3, v4
	v_mul_f32_e32 v7, v4, v4
	s_waitcnt lgkmcnt(0)
	v_lshlrev_b32_e32 v6, 16, v6
	v_fmac_f32_e32 v7, v2, v2
	v_fma_f32 v6, -v8, v3, v6
	v_lshlrev_b32_e32 v5, 16, v5
	v_mul_f32_e32 v8, v210, v12
	v_fmac_f32_e32 v7, v6, v6
	v_fma_f32 v3, -v8, v3, v5
	v_fmac_f32_e32 v7, v3, v3
	s_nop 1
	ds_write_b16 v216, v1 offset:4992
	s_waitcnt lgkmcnt(1)
	v_add_f32_dpp v5, v7, v7 quad_perm:[1,0,3,2] row_mask:0xf bank_mask:0xf
	s_nop 1
	s_waitcnt lgkmcnt(0)
	v_add_f32_dpp v5, v5, v5 quad_perm:[2,3,0,1] row_mask:0xf bank_mask:0xf
	s_nop 1
	s_waitcnt lgkmcnt(0)
	v_add_f32_dpp v5, v5, v5 row_half_mirror row_mask:0xf bank_mask:0xf
	s_nop 1
	s_waitcnt lgkmcnt(0)
	v_add_f32_dpp v5, v5, v5 row_mirror row_mask:0xf bank_mask:0xf
	ds_bpermute_b32 v7, v83, v5
	s_waitcnt lgkmcnt(0)
	v_add_f32_e32 v5, v5, v7
	v_fmamk_f32 v5, v5, 0x3c000000, v198
	v_mul_f32_e32 v7, 0x4f800000, v5
	v_cmp_gt_f32_e32 vcc, s72, v5
	s_nop 1
	v_cndmask_b32_e32 v5, v5, v7, vcc
	v_sqrt_f32_e32 v7, v5
	s_nop 0
	v_add_u32_e32 v8, -1, v7
	v_fma_f32 v9, -v8, v7, v5
	v_cmp_ge_f32_e64 s[0:1], 0, v9
	v_add_u32_e32 v9, 1, v7
	s_nop 0
	v_cndmask_b32_e64 v8, v7, v8, s[0:1]
	v_fma_f32 v7, -v9, v7, v5
	v_cmp_lt_f32_e64 s[0:1], 0, v7
	s_nop 1
	v_cndmask_b32_e64 v7, v8, v9, s[0:1]
	v_mul_f32_e32 v8, 0x37800000, v7
	v_cndmask_b32_e32 v7, v7, v8, vcc
	v_cmp_class_f32_e32 vcc, v5, v199
	s_nop 1
	v_cndmask_b32_e32 v5, v7, v5, vcc
	v_div_scale_f32 v7, s[0:1], v5, v5, 1.0
	v_rcp_f32_e32 v8, v7
	s_nop 0
	v_fma_f32 v1, -v7, v8, 1.0
	v_fmac_f32_e32 v8, v1, v8
	v_div_scale_f32 v1, vcc, 1.0, v5, 1.0
	v_mul_f32_e32 v9, v1, v8
	v_fma_f32 v10, -v7, v9, v1
	v_fmac_f32_e32 v9, v10, v8
	v_fma_f32 v1, -v7, v9, v1
	v_div_fmas_f32 v1, v1, v8, v9
	v_div_fixup_f32 v1, v1, v5, 1.0
	v_mul_f32_e32 v2, v2, v1
	v_mul_f32_e32 v2, v48, v2
	v_cvt_pk_bf16_f32 v2, v2, v133
	ds_write_b16 v222, v2 offset:6272
	v_mul_f32_e32 v2, v4, v1
	v_mul_f32_e32 v2, v76, v2
	v_cvt_pk_bf16_f32 v2, v2, v133
	ds_write_b16 v221, v2 offset:6272
	v_mul_f32_e32 v2, v6, v1
	v_mul_f32_e32 v2, v16, v2
	v_mul_f32_e32 v1, v3, v1
	v_cvt_pk_bf16_f32 v2, v2, v133
	v_mul_f32_e32 v1, v0, v1
	ds_write_b16 v222, v2 offset:6144
	v_cvt_pk_bf16_f32 v1, v1, v133
	ds_read_u16 v2, v220 offset:6528
	v_rcp_f32_e32 v3, v65
	ds_read_u16 v4, v219 offset:6528
	ds_read_u16 v5, v219 offset:6400
	ds_read_u16 v6, v220 offset:6400
	v_mul_f32_e32 v7, v210, v61
	v_mul_f32_e32 v8, v210, v29
	s_waitcnt lgkmcnt(3)
	v_lshlrev_b32_e32 v2, 16, v2
	v_fma_f32 v2, -v7, v3, v2
	s_waitcnt lgkmcnt(2)
	v_lshlrev_b32_e32 v4, 16, v4
	v_mul_f32_e32 v7, v210, v45
	v_fma_f32 v4, -v7, v3, v4
	v_mul_f32_e32 v7, v4, v4
	s_waitcnt lgkmcnt(0)
	v_lshlrev_b32_e32 v6, 16, v6
	v_fmac_f32_e32 v7, v2, v2
	v_fma_f32 v6, -v8, v3, v6
	v_lshlrev_b32_e32 v5, 16, v5
	v_mul_f32_e32 v8, v210, v13
	v_fmac_f32_e32 v7, v6, v6
	v_fma_f32 v3, -v8, v3, v5
	v_fmac_f32_e32 v7, v3, v3
	s_nop 1
	ds_write_b16 v221, v1 offset:6144
	s_waitcnt lgkmcnt(1)
	v_add_f32_dpp v5, v7, v7 quad_perm:[1,0,3,2] row_mask:0xf bank_mask:0xf
	s_nop 1
	s_waitcnt lgkmcnt(0)
	v_add_f32_dpp v5, v5, v5 quad_perm:[2,3,0,1] row_mask:0xf bank_mask:0xf
	s_nop 1
	s_waitcnt lgkmcnt(0)
	v_add_f32_dpp v5, v5, v5 row_half_mirror row_mask:0xf bank_mask:0xf
	s_nop 1
	s_waitcnt lgkmcnt(0)
	v_add_f32_dpp v5, v5, v5 row_mirror row_mask:0xf bank_mask:0xf
	ds_bpermute_b32 v7, v83, v5
	s_waitcnt lgkmcnt(0)
	v_add_f32_e32 v5, v5, v7
	v_fmamk_f32 v5, v5, 0x3c000000, v198
	v_mul_f32_e32 v7, 0x4f800000, v5
	v_cmp_gt_f32_e32 vcc, s72, v5
	s_nop 1
	v_cndmask_b32_e32 v5, v5, v7, vcc
	v_sqrt_f32_e32 v7, v5
	s_nop 0
	v_add_u32_e32 v8, -1, v7
	v_fma_f32 v9, -v8, v7, v5
	v_cmp_ge_f32_e64 s[0:1], 0, v9
	v_add_u32_e32 v9, 1, v7
	s_nop 0
	v_cndmask_b32_e64 v8, v7, v8, s[0:1]
	v_fma_f32 v7, -v9, v7, v5
	v_cmp_lt_f32_e64 s[0:1], 0, v7
	s_nop 1
	v_cndmask_b32_e64 v7, v8, v9, s[0:1]
	v_mul_f32_e32 v8, 0x37800000, v7
	v_cndmask_b32_e32 v7, v7, v8, vcc
	v_cmp_class_f32_e32 vcc, v5, v199
	s_nop 1
	v_cndmask_b32_e32 v5, v7, v5, vcc
	v_div_scale_f32 v7, s[0:1], v5, v5, 1.0
	v_rcp_f32_e32 v8, v7
	s_nop 0
	v_fma_f32 v1, -v7, v8, 1.0
	v_fmac_f32_e32 v8, v1, v8
	v_div_scale_f32 v1, vcc, 1.0, v5, 1.0
	v_mul_f32_e32 v9, v1, v8
	v_fma_f32 v10, -v7, v9, v1
	v_fmac_f32_e32 v9, v10, v8
	v_fma_f32 v1, -v7, v9, v1
	v_div_fmas_f32 v1, v1, v8, v9
	v_div_fixup_f32 v1, v1, v5, 1.0
	v_mul_f32_e32 v2, v2, v1
	v_mul_f32_e32 v2, v48, v2
	v_cvt_pk_bf16_f32 v2, v2, v133
	ds_write_b16 v220, v2 offset:6528
	v_mul_f32_e32 v2, v4, v1
	v_mul_f32_e32 v2, v76, v2
	v_cvt_pk_bf16_f32 v2, v2, v133
	ds_write_b16 v219, v2 offset:6528
	v_mul_f32_e32 v2, v6, v1
	v_mul_f32_e32 v2, v16, v2
	v_mul_f32_e32 v1, v3, v1
	v_cvt_pk_bf16_f32 v2, v2, v133
	v_mul_f32_e32 v1, v0, v1
	ds_write_b16 v220, v2 offset:6400
	v_cvt_pk_bf16_f32 v1, v1, v133
	ds_read_u16 v2, v218 offset:6784
	v_rcp_f32_e32 v3, v66
	ds_read_u16 v4, v217 offset:6784
	ds_read_u16 v5, v217 offset:6656
	ds_read_u16 v6, v218 offset:6656
	v_mul_f32_e32 v7, v210, v62
	v_mul_f32_e32 v8, v210, v30
	s_waitcnt lgkmcnt(3)
	v_lshlrev_b32_e32 v2, 16, v2
	v_fma_f32 v2, -v7, v3, v2
	s_waitcnt lgkmcnt(2)
	v_lshlrev_b32_e32 v4, 16, v4
	v_mul_f32_e32 v7, v210, v46
	v_fma_f32 v4, -v7, v3, v4
	v_mul_f32_e32 v7, v4, v4
	s_waitcnt lgkmcnt(0)
	v_lshlrev_b32_e32 v6, 16, v6
	v_fmac_f32_e32 v7, v2, v2
	v_fma_f32 v6, -v8, v3, v6
	v_lshlrev_b32_e32 v5, 16, v5
	v_mul_f32_e32 v8, v210, v14
	v_fmac_f32_e32 v7, v6, v6
	v_fma_f32 v3, -v8, v3, v5
	v_fmac_f32_e32 v7, v3, v3
	s_nop 1
	ds_write_b16 v219, v1 offset:6400
	s_waitcnt lgkmcnt(1)
	v_add_f32_dpp v5, v7, v7 quad_perm:[1,0,3,2] row_mask:0xf bank_mask:0xf
	s_nop 1
	s_waitcnt lgkmcnt(0)
	v_add_f32_dpp v5, v5, v5 quad_perm:[2,3,0,1] row_mask:0xf bank_mask:0xf
	s_nop 1
	s_waitcnt lgkmcnt(0)
	v_add_f32_dpp v5, v5, v5 row_half_mirror row_mask:0xf bank_mask:0xf
	s_nop 1
	s_waitcnt lgkmcnt(0)
	v_add_f32_dpp v5, v5, v5 row_mirror row_mask:0xf bank_mask:0xf
	ds_bpermute_b32 v7, v83, v5
	s_waitcnt lgkmcnt(0)
	v_add_f32_e32 v5, v5, v7
	v_fmamk_f32 v5, v5, 0x3c000000, v198
	v_mul_f32_e32 v7, 0x4f800000, v5
	v_cmp_gt_f32_e32 vcc, s72, v5
	s_nop 1
	v_cndmask_b32_e32 v5, v5, v7, vcc
	v_sqrt_f32_e32 v7, v5
	s_nop 0
	v_add_u32_e32 v8, -1, v7
	v_fma_f32 v9, -v8, v7, v5
	v_cmp_ge_f32_e64 s[0:1], 0, v9
	v_add_u32_e32 v9, 1, v7
	s_nop 0
	v_cndmask_b32_e64 v8, v7, v8, s[0:1]
	v_fma_f32 v7, -v9, v7, v5
	v_cmp_lt_f32_e64 s[0:1], 0, v7
	s_nop 1
	v_cndmask_b32_e64 v7, v8, v9, s[0:1]
	v_mul_f32_e32 v8, 0x37800000, v7
	v_cndmask_b32_e32 v7, v7, v8, vcc
	v_cmp_class_f32_e32 vcc, v5, v199
	s_nop 1
	v_cndmask_b32_e32 v5, v7, v5, vcc
	v_div_scale_f32 v7, s[0:1], v5, v5, 1.0
	v_rcp_f32_e32 v8, v7
	s_nop 0
	v_fma_f32 v1, -v7, v8, 1.0
	v_fmac_f32_e32 v8, v1, v8
	v_div_scale_f32 v1, vcc, 1.0, v5, 1.0
	v_mul_f32_e32 v9, v1, v8
	v_fma_f32 v10, -v7, v9, v1
	v_fmac_f32_e32 v9, v10, v8
	v_fma_f32 v1, -v7, v9, v1
	v_div_fmas_f32 v1, v1, v8, v9
	v_div_fixup_f32 v1, v1, v5, 1.0
	v_mul_f32_e32 v2, v2, v1
	v_mul_f32_e32 v2, v48, v2
	v_cvt_pk_bf16_f32 v2, v2, v133
	ds_write_b16 v218, v2 offset:6784
	v_mul_f32_e32 v2, v4, v1
	v_mul_f32_e32 v2, v76, v2
	v_cvt_pk_bf16_f32 v2, v2, v133
	ds_write_b16 v217, v2 offset:6784
	v_mul_f32_e32 v2, v6, v1
	v_mul_f32_e32 v2, v16, v2
	v_mul_f32_e32 v1, v3, v1
	v_cvt_pk_bf16_f32 v2, v2, v133
	v_mul_f32_e32 v1, v0, v1
	ds_write_b16 v218, v2 offset:6656
	v_cvt_pk_bf16_f32 v1, v1, v133
	ds_read_u16 v2, v215 offset:7040
	v_rcp_f32_e32 v3, v67
	ds_read_u16 v4, v216 offset:7040
	ds_read_u16 v5, v216 offset:6912
	ds_read_u16 v6, v215 offset:6912
	v_mul_f32_e32 v7, v210, v63
	v_mul_f32_e32 v8, v210, v31
	s_waitcnt lgkmcnt(3)
	v_lshlrev_b32_e32 v2, 16, v2
	v_fma_f32 v2, -v7, v3, v2
	s_waitcnt lgkmcnt(2)
	v_lshlrev_b32_e32 v4, 16, v4
	v_mul_f32_e32 v7, v210, v47
	v_fma_f32 v4, -v7, v3, v4
	v_mul_f32_e32 v7, v4, v4
	s_waitcnt lgkmcnt(0)
	v_lshlrev_b32_e32 v6, 16, v6
	v_fmac_f32_e32 v7, v2, v2
	v_fma_f32 v6, -v8, v3, v6
	v_lshlrev_b32_e32 v5, 16, v5
	v_mul_f32_e32 v8, v210, v15
	v_fmac_f32_e32 v7, v6, v6
	v_fma_f32 v3, -v8, v3, v5
	v_fmac_f32_e32 v7, v3, v3
	s_nop 1
	ds_write_b16 v217, v1 offset:6656
	s_waitcnt lgkmcnt(1)
	v_add_f32_dpp v5, v7, v7 quad_perm:[1,0,3,2] row_mask:0xf bank_mask:0xf
	s_nop 1
	s_waitcnt lgkmcnt(0)
	v_add_f32_dpp v5, v5, v5 quad_perm:[2,3,0,1] row_mask:0xf bank_mask:0xf
	s_nop 1
	s_waitcnt lgkmcnt(0)
	v_add_f32_dpp v5, v5, v5 row_half_mirror row_mask:0xf bank_mask:0xf
	s_nop 1
	s_waitcnt lgkmcnt(0)
	v_add_f32_dpp v5, v5, v5 row_mirror row_mask:0xf bank_mask:0xf
	ds_bpermute_b32 v7, v83, v5
	s_waitcnt lgkmcnt(0)
	v_add_f32_e32 v5, v5, v7
	v_fmamk_f32 v5, v5, 0x3c000000, v198
	v_mul_f32_e32 v7, 0x4f800000, v5
	v_cmp_gt_f32_e32 vcc, s72, v5
	s_nop 1
	v_cndmask_b32_e32 v5, v5, v7, vcc
	v_sqrt_f32_e32 v7, v5
	s_nop 0
	v_add_u32_e32 v8, -1, v7
	v_fma_f32 v9, -v8, v7, v5
	v_cmp_ge_f32_e64 s[0:1], 0, v9
	v_add_u32_e32 v9, 1, v7
	s_nop 0
	v_cndmask_b32_e64 v8, v7, v8, s[0:1]
	v_fma_f32 v7, -v9, v7, v5
	v_cmp_lt_f32_e64 s[0:1], 0, v7
	s_nop 1
	v_cndmask_b32_e64 v7, v8, v9, s[0:1]
	v_mul_f32_e32 v8, 0x37800000, v7
	v_cndmask_b32_e32 v7, v7, v8, vcc
	v_cmp_class_f32_e32 vcc, v5, v199
	s_nop 1
	v_cndmask_b32_e32 v5, v7, v5, vcc
	v_div_scale_f32 v7, s[0:1], v5, v5, 1.0
	v_rcp_f32_e32 v8, v7
	s_nop 0
	v_fma_f32 v1, -v7, v8, 1.0
	v_fmac_f32_e32 v8, v1, v8
	v_div_scale_f32 v1, vcc, 1.0, v5, 1.0
	v_mul_f32_e32 v9, v1, v8
	v_fma_f32 v10, -v7, v9, v1
	v_fmac_f32_e32 v9, v10, v8
	v_fma_f32 v1, -v7, v9, v1
	v_div_fmas_f32 v1, v1, v8, v9
	v_div_fixup_f32 v1, v1, v5, 1.0
	v_mul_f32_e32 v2, v2, v1
	v_mul_f32_e32 v2, v48, v2
	v_cvt_pk_bf16_f32 v2, v2, v133
	ds_write_b16 v215, v2 offset:7040
	v_mul_f32_e32 v2, v4, v1
	v_mul_f32_e32 v2, v76, v2
	v_cvt_pk_bf16_f32 v2, v2, v133
	ds_write_b16 v216, v2 offset:7040
	v_mul_f32_e32 v2, v6, v1
	v_mul_f32_e32 v1, v3, v1
	v_mul_f32_e32 v2, v16, v2
	v_mul_f32_e32 v0, v0, v1
	v_cvt_pk_bf16_f32 v2, v2, v133
	ds_write_b16 v215, v2 offset:6912
	v_cvt_pk_bf16_f32 v0, v0, v133
	ds_write_b16 v216, v0 offset:6912
	s_waitcnt lgkmcnt(0)
	ds_read_b128 v[0:3], v200
	v_lshl_add_u64 v[8:9], s[62:63], 0, v[134:135]
	v_lshl_add_u64 v[10:11], v[152:153], 0, s[2:3]
	v_or_b32_e32 v4, v8, v128
	v_mad_u64_u32 v[12:13], s[0:1], v4, s70, v[10:11]
	v_mul_lo_u32 v9, v9, s70
	ds_read_b128 v[4:7], v201
	v_add_u32_e32 v13, v9, v13
	s_waitcnt lgkmcnt(1)
	global_store_dwordx4 v[12:13], v[0:3], off
	s_nop 1
	v_or_b32_e32 v0, v8, v136
	v_mad_u64_u32 v[0:1], s[0:1], v0, s70, v[10:11]
	v_add_u32_e32 v1, v9, v1
	s_waitcnt lgkmcnt(0)
	global_store_dwordx4 v[0:1], v[4:7], off
	ds_read_b128 v[0:3], v202
	s_nop 0
	v_or_b32_e32 v4, v8, v138
	v_mad_u64_u32 v[12:13], s[0:1], v4, s70, v[10:11]
	ds_read_b128 v[4:7], v203
	v_add_u32_e32 v13, v9, v13
	s_waitcnt lgkmcnt(1)
	global_store_dwordx4 v[12:13], v[0:3], off
	s_nop 1
	v_or_b32_e32 v0, v8, v140
	v_mad_u64_u32 v[0:1], s[0:1], v0, s70, v[10:11]
	v_add_u32_e32 v1, v9, v1
	s_waitcnt lgkmcnt(0)
	global_store_dwordx4 v[0:1], v[4:7], off
	ds_read_b128 v[0:3], v204
	s_nop 0
	v_or_b32_e32 v4, v8, v142
	v_mad_u64_u32 v[12:13], s[0:1], v4, s70, v[10:11]
	ds_read_b128 v[4:7], v205
	v_add_u32_e32 v13, v9, v13
	s_waitcnt lgkmcnt(1)
	global_store_dwordx4 v[12:13], v[0:3], off
	s_nop 1
	v_or_b32_e32 v0, v8, v144
	v_mad_u64_u32 v[0:1], s[0:1], v0, s70, v[10:11]
	v_add_u32_e32 v1, v9, v1
	s_waitcnt lgkmcnt(0)
	global_store_dwordx4 v[0:1], v[4:7], off
	ds_read_b128 v[0:3], v206
	s_nop 0
	v_or_b32_e32 v4, v8, v146
	v_mad_u64_u32 v[12:13], s[0:1], v4, s70, v[10:11]
	ds_read_b128 v[4:7], v207
	v_add_u32_e32 v13, v9, v13
	s_waitcnt lgkmcnt(1)
	global_store_dwordx4 v[12:13], v[0:3], off
	s_nop 1
	v_or_b32_e32 v0, v8, v148
	v_mad_u64_u32 v[0:1], s[0:1], v0, s70, v[10:11]
	v_add_u32_e32 v1, v9, v1
	s_waitcnt lgkmcnt(0)
	global_store_dwordx4 v[0:1], v[4:7], off
	s_cbranch_scc1 .LBB0_1068
